# speedup vs baseline: 1.0001x; 1.0001x over previous
; #define WAIT_V(n) asm volatile("s_waitcnt vmcnt(" #n ")":::"memory")
; #define BAR __builtin_amdgcn_s_barrier()
; #define STAGE_A(b,h,kt) do{ unsigned char* _d = SA(b,h) + wbase; \
;     if constexpr (BLK) { const char* _s = baseA + ((size_t)(h)*(K/64) + (kt)) * 16384; GLDS(_s + voa, _d); GLDS(_s + 8192 + voa, _d + 8192); } \
;     else { const char* _s = baseA + ((size_t)(h)*128*K + (kt)*64) * 2; GLDS(_s + voa, _d); GLDS(_s + (size_t)128*K + voa, _d + 8192); } }while(0)
; #define STAGE_B(b,h,kt) do{ unsigned char* _d = SB(b,h) + wbase; \
;     if constexpr (BLK) { const char* _s = ((h)?baseB1:baseB0) + (size_t)(kt) * 16384; GLDS(_s + voa, _d); GLDS(_s + 8192 + voa, _d + 8192); } \
;     else { const char* _s = ((h)?baseB1:baseB0) + (kt)*128; GLDS(_s + voa, _d); GLDS(_s + (size_t)128*K + voa, _d + 8192); } }while(0)
; template <int K, int EPI, bool MIX = false>
; __device__ __forceinline__ void gemm_phase(const Params& p, const u16* __restrict__ A, const u16* __restrict__ Bt,
;                            const float* __restrict__ rs_in, float* __restrict__ ssq_out, float alpha, bool rev = false) {
;     ...
;   int tid = threadIdx.x;
;   asm volatile("" : "+v"(tid));
;   const int wid = __builtin_amdgcn_readfirstlane(tid >> 6);
;   const int lane = tid & 63, wr = wid >> 2, wc = wid & 3, fr = lane & 15, fq = lane >> 4;
;   const int wbase = wid * 1024;
;   int koff[2];
;   koff[0] = lds_off32(fr, fq); koff[1] = lds_off32(fr, 4 + fq);
;   int it = 0;
;   int id = item_id(0);
;   if (id >= ntiles) return;
;   if (rev) id = ntiles - 1 - id;
;   int pm, pn;
;   const char *baseA, *baseB0, *baseB1;
;   unsigned voa;
;   {
;     const int R = tid >> 3, C = ((tid & 7) ^ ((R >> 1) & 7)) * 8;
;     voa = (unsigned)(R * (BLK ? 64 : K) + C) * 2u;
;   }
;     ...
;   SETUP_TILE();
;   STAGE_B(0,0,0); STAGE_A(0,0,0); STAGE_B(0,1,0); STAGE_A(0,1,0);
;   if (wr == 1) BAR;
;   WAIT_V(4); BAR;
;   STAGE_B(1,0,1); STAGE_A(1,0,1); STAGE_B(1,1,1);
;   WAIT_V(6); BAR;
.LBB0_86:
	s_add_i32 s44, s22, 0x18000
	s_mov_b64 s[14:15], 0x80
	v_lshl_add_u64 v[10:11], v[0:1], 0, s[14:15]
	s_mov_b32 m0, s44
	s_mov_b64 s[16:17], 0x40080
	s_add_i32 s45, s22, 0x1a000
	s_waitcnt vmcnt(4)
	s_barrier
	global_load_lds_dwordx4 v[10:11], off
	v_lshl_add_u64 v[0:1], v[0:1], 0, s[16:17]
	s_mov_b32 m0, s45
	s_add_i32 s46, s22, 0x8000
	global_load_lds_dwordx4 v[0:1], off
	v_lshl_add_u64 v[0:1], v[2:3], 0, s[14:15]
	s_mov_b32 m0, s46
	s_add_i32 s47, s22, 0xa000
	global_load_lds_dwordx4 v[0:1], off
	v_lshl_add_u64 v[0:1], v[2:3], 0, s[16:17]
	s_mov_b32 m0, s47
	s_add_i32 s48, s22, 0x1c000
	global_load_lds_dwordx4 v[0:1], off
	v_lshl_add_u64 v[0:1], v[4:5], 0, s[14:15]
	s_mov_b32 m0, s48
	s_add_i32 s49, s22, 0x1e000
	global_load_lds_dwordx4 v[0:1], off
	v_lshl_add_u64 v[0:1], v[4:5], 0, s[16:17]
	s_mov_b32 m0, s49
	s_and_b32 s20, s18, 3
	global_load_lds_dwordx4 v[0:1], off
	s_lshl_b32 s18, s20, 12
	s_or_b32 s24, s18, 0x10000
	s_lshl_b32 s25, s5, 13
	s_or_b32 s26, s18, 0x14000
	s_or_b32 s28, s18, 0x18000
	s_or_b32 s29, s18, 0x1c000
	s_lshl_b32 s50, s5, 6
	v_and_b32_e32 v221, 15, v8
	v_bfe_u32 v0, v8, 4, 2
	v_bfe_u32 v2, v8, 1, 3
	s_cmpk_lt_u32 s4, 0x100
	v_lshlrev_b32_e32 v1, 7, v221
	v_xor_b32_e32 v3, v0, v2
	v_bitop3_b32 v0, v0, v2, 4 bitop3:0x36
	s_waitcnt vmcnt(6)
	s_cselect_b64 s[18:19], -1, 0
	s_lshl_b32 s51, s20, 5
	v_lshl_or_b32 v3, v3, 4, v1
	v_lshl_or_b32 v0, v0, 4, v1
	s_and_b32 s4, s51, 32
	s_mov_b32 s21, 0
	v_and_b32_e32 v220, 63, v8
	v_add_u32_e32 v212, v7, v6
	v_mov_b32_e32 v213, v211
	v_add_u32_e32 v222, s24, v3
	v_add_u32_e32 v223, s24, v0
	v_add_u32_e32 v224, s25, v3
	v_add_u32_e32 v225, s25, v0
	s_add_i32 s74, s22, 0xc000
	s_add_i32 s75, s22, 0xe000
	v_add_u32_e32 v226, s26, v3
	v_add_u32_e32 v227, s26, v0
	s_mov_b64 s[24:25], 0x100
	s_mov_b64 s[26:27], 0x40100
	v_add_u32_e32 v228, s28, v3
	v_add_u32_e32 v229, s28, v0
	v_add_u32_e32 v232, s29, v3
	v_add_u32_e32 v233, s29, v0
	s_mov_b64 s[28:29], 0x180
	s_mov_b64 s[36:37], 0x40180
	v_mov_b32_e32 v234, 0x358637bd
	s_mov_b32 s78, 0x800000
	s_lshl_b32 s20, s4, 1
	s_mov_b32 s79, s21
	v_readlane_b32 s76, v255, 6
	s_barrier
	v_readfirstlane_b32 vcc_lo, v230
	s_nop 3
	s_cmpk_ge_u32 vcc_lo, 0x100
	s_cbranch_scc1 .Lprio_p1
	s_setprio 1
.Lprio_p1:
	s_mov_b64 vcc, exec
	s_branch .LBB0_88

; #define SCHED __builtin_amdgcn_sched_barrier(0)
; template <int K, int EPI, bool MIX = false>
; __device__ __forceinline__ void gemm_phase(const Params& p, const u16* __restrict__ A, const u16* __restrict__ Bt,
;                            const float* __restrict__ rs_in, float* __restrict__ ssq_out, float alpha, bool rev = false) {
;     ...
;     if (!more) break;
;     asm volatile("" ::: "memory");
;     SCHED;
;   }
;     ...
; }
; __global__ void __launch_bounds__(NTHR) fwd_megakernel(Params p) {
;     ...
;   run_phase<0>(p); grid.sync();
;   run_phase<1>(p); grid.sync();
.LBB0_112:
	s_setprio 0
	s_waitcnt vmcnt(0) lgkmcnt(0)
	s_barrier
	s_mov_b64 s[0:1], exec
	v_readlane_b32 s2, v255, 1
	v_readlane_b32 s3, v255, 2
	s_and_b64 s[2:3], s[0:1], s[2:3]
	s_mov_b64 exec, s[2:3]
	s_cbranch_execz .LBB0_122
	buffer_wbl2 sc1
	s_waitcnt vmcnt(0)
	v_readlane_b32 s2, v254, 24
	v_readlane_b32 s3, v254, 25
	v_readlane_b32 s4, v255, 3
	s_load_dword s5, s[72:73], 0x0
	s_nop 3
	s_add_u32 s2, s2, 0x10000000
	s_addc_u32 s3, s3, 0
	s_and_b32 s4, s4, 7
	s_lshl_b32 s4, s4, 8
	s_add_i32 s4, s4, 0x100
	v_mov_b32_e32 v2, 0
	v_mov_b32_e32 v3, 1
	v_mov_b32_e32 v0, s4
	s_nop 3
	global_atomic_add v3, v2, v3, s[2:3] sc0 sc1
	s_waitcnt lgkmcnt(0)
	s_mul_i32 s5, s5, 1
	s_add_i32 s5, s5, -1
	s_waitcnt vmcnt(0)
	v_readfirstlane_b32 s4, v3
	s_nop 3
	s_cmp_lg_u32 s4, s5
	s_cbranch_scc1 .Lfb1_poll0
	v_mov_b32_e32 v1, 1
	global_atomic_add v2, v1, s[2:3] offset:256 sc1
	global_atomic_add v2, v1, s[2:3] offset:512 sc1
	global_atomic_add v2, v1, s[2:3] offset:768 sc1
	global_atomic_add v2, v1, s[2:3] offset:1024 sc1
	global_atomic_add v2, v1, s[2:3] offset:1280 sc1
	global_atomic_add v2, v1, s[2:3] offset:1536 sc1
	global_atomic_add v2, v1, s[2:3] offset:1792 sc1
	global_atomic_add v2, v1, s[2:3] offset:2048 sc1
	s_branch .Lfb1_done

; #define WAIT_V(n) asm volatile("s_waitcnt vmcnt(" #n ")":::"memory")
; #define BAR __builtin_amdgcn_s_barrier()
; #define STAGE_A(b,h,kt) do{ unsigned char* _d = SA(b,h) + wbase; \
;     if constexpr (BLK) { const char* _s = baseA + ((size_t)(h)*(K/64) + (kt)) * 16384; GLDS(_s + voa, _d); GLDS(_s + 8192 + voa, _d + 8192); } \
;     else { const char* _s = baseA + ((size_t)(h)*128*K + (kt)*64) * 2; GLDS(_s + voa, _d); GLDS(_s + (size_t)128*K + voa, _d + 8192); } }while(0)
; #define STAGE_B(b,h,kt) do{ unsigned char* _d = SB(b,h) + wbase; \
;     if constexpr (BLK) { const char* _s = ((h)?baseB1:baseB0) + (size_t)(kt) * 16384; GLDS(_s + voa, _d); GLDS(_s + 8192 + voa, _d + 8192); } \
;     else { const char* _s = ((h)?baseB1:baseB0) + (kt)*128; GLDS(_s + voa, _d); GLDS(_s + (size_t)128*K + voa, _d + 8192); } }while(0)
; template <int K, int EPI, bool MIX = false>
; __device__ __forceinline__ void gemm_phase(const Params& p, const u16* __restrict__ A, const u16* __restrict__ Bt,
;                            const float* __restrict__ rs_in, float* __restrict__ ssq_out, float alpha, bool rev = false) {
;     ...
;   int tid = threadIdx.x;
;   asm volatile("" : "+v"(tid));
;   const int wid = __builtin_amdgcn_readfirstlane(tid >> 6);
;   const int lane = tid & 63, wr = wid >> 2, wc = wid & 3, fr = lane & 15, fq = lane >> 4;
;   const int wbase = wid * 1024;
;   int koff[2];
;   koff[0] = lds_off32(fr, fq); koff[1] = lds_off32(fr, 4 + fq);
;   int it = 0;
;   int id = item_id(0);
;   if (id >= ntiles) return;
;   if (rev) id = ntiles - 1 - id;
;   int pm, pn;
;   const char *baseA, *baseB0, *baseB1;
;   unsigned voa;
;   {
;     const int R = tid >> 3, C = ((tid & 7) ^ ((R >> 1) & 7)) * 8;
;     voa = (unsigned)(R * (BLK ? 64 : K) + C) * 2u;
;   }
;     ...
;   SETUP_TILE();
;   STAGE_B(0,0,0); STAGE_A(0,0,0); STAGE_B(0,1,0); STAGE_A(0,1,0);
;   if (wr == 1) BAR;
;   WAIT_V(4); BAR;
;   STAGE_B(1,0,1); STAGE_A(1,0,1); STAGE_B(1,1,1);
;   WAIT_V(6); BAR;
.LBB0_125:
	s_add_i32 s43, s22, 0x18000
	s_mov_b64 s[14:15], 0x4000
	v_lshl_add_u64 v[8:9], v[0:1], 0, s[14:15]
	s_mov_b32 m0, s43
	s_mov_b64 s[16:17], 0x6000
	s_add_i32 s44, s22, 0x1a000
	s_waitcnt vmcnt(4)
	s_barrier
	global_load_lds_dwordx4 v[8:9], off
	v_lshl_add_u64 v[8:9], v[0:1], 0, s[16:17]
	s_mov_b32 m0, s44
	s_add_i32 s45, s22, 0x8000
	global_load_lds_dwordx4 v[8:9], off
	v_lshl_add_u64 v[8:9], v[2:3], 0, s[14:15]
	s_mov_b32 m0, s45
	s_add_i32 s48, s22, 0xa000
	global_load_lds_dwordx4 v[8:9], off
	v_lshl_add_u64 v[2:3], v[2:3], 0, s[16:17]
	s_mov_b32 m0, s48
	s_add_i32 s49, s22, 0x1c000
	s_mov_b64 s[18:19], 0x164000
	global_load_lds_dwordx4 v[2:3], off
	v_lshl_add_u64 v[2:3], v[0:1], 0, s[18:19]
	s_mov_b32 m0, s49
	s_mov_b64 s[20:21], 0x166000
	s_add_i32 s50, s22, 0x1e000
	global_load_lds_dwordx4 v[2:3], off
	v_lshl_add_u64 v[0:1], v[0:1], 0, s[20:21]
	s_mov_b32 m0, s50
	s_and_b32 s26, s24, 3
	global_load_lds_dwordx4 v[0:1], off
	s_lshl_b32 s24, s26, 12
	v_and_b32_e32 v0, 15, v6
	v_bfe_u32 v1, v6, 4, 2
	v_bfe_u32 v2, v6, 1, 3
	s_or_b32 s28, s24, 0x10000
	s_lshl_b32 s29, s5, 13
	s_or_b32 s36, s24, 0x14000
	s_or_b32 s38, s24, 0x18000
	s_or_b32 s39, s24, 0x1c000
	v_lshlrev_b32_e32 v0, 7, v0
	v_xor_b32_e32 v3, v1, v2
	v_bitop3_b32 v1, v1, v2, 4 bitop3:0x36
	s_waitcnt vmcnt(6)
	s_cmpk_lt_u32 s4, 0x100
	v_lshl_or_b32 v3, v3, 4, v0
	v_lshl_or_b32 v0, v1, 4, v0
	s_cselect_b64 s[24:25], -1, 0
	s_lshl_b32 s4, s26, 5
	s_mov_b32 s27, 0
	v_and_b32_e32 v218, 63, v6
	s_lshl_b32 s51, s5, 6
	v_add_u32_e32 v210, v5, v4
	v_mov_b32_e32 v211, v209
	v_add_u32_e32 v219, s28, v3
	v_add_u32_e32 v220, s28, v0
	v_add_u32_e32 v221, s29, v3
	v_add_u32_e32 v222, s29, v0
	s_add_i32 s74, s22, 0xc000
	s_add_i32 s75, s22, 0xe000
	v_add_u32_e32 v223, s36, v3
	v_add_u32_e32 v224, s36, v0
	s_mov_b64 s[28:29], 0x8000
	s_mov_b64 s[36:37], 0xa000
	v_add_u32_e32 v225, s38, v3
	v_add_u32_e32 v226, s38, v0
	v_add_u32_e32 v227, s39, v3
	v_add_u32_e32 v228, s39, v0
	s_mov_b64 s[38:39], 0xc000
	s_mov_b64 s[40:41], 0xe000
	v_mbcnt_hi_u32_b32 v229, -1, v231
	s_lshl_b32 s26, s4, 1
	s_mov_b32 s78, s27
	s_barrier
	v_readfirstlane_b32 vcc_lo, v230
	s_nop 3
	s_cmpk_ge_u32 vcc_lo, 0x100
	s_cbranch_scc1 .Lprio_p2
	s_setprio 1

; #define SCHED __builtin_amdgcn_sched_barrier(0)
; template <int K, int EPI, bool MIX = false>
; __device__ __forceinline__ void gemm_phase(const Params& p, const u16* __restrict__ A, const u16* __restrict__ Bt,
;                            const float* __restrict__ rs_in, float* __restrict__ ssq_out, float alpha, bool rev = false) {
;     ...
;     if (!more) break;
;     asm volatile("" ::: "memory");
;     SCHED;
;   }
;     ...
; }
; __global__ void __launch_bounds__(NTHR) fwd_megakernel(Params p) {
;     ...
;   run_phase<1>(p); grid.sync();
;   run_phase<2>(p); grid.sync();
.LBB0_167:
	s_setprio 0
	s_waitcnt vmcnt(0) lgkmcnt(0)
	s_barrier
	s_mov_b64 s[0:1], exec
	v_readlane_b32 s2, v255, 1
	v_readlane_b32 s3, v255, 2
	s_and_b64 s[2:3], s[0:1], s[2:3]
	s_mov_b64 exec, s[2:3]
	s_cbranch_execz .LBB0_177
	buffer_wbl2 sc1
	s_waitcnt vmcnt(0)
	v_readlane_b32 s2, v254, 24
	v_readlane_b32 s3, v254, 25
	v_readlane_b32 s4, v255, 3
	s_load_dword s5, s[72:73], 0x0
	s_nop 3
	s_add_u32 s2, s2, 0x10000000
	s_addc_u32 s3, s3, 0
	s_and_b32 s4, s4, 7
	s_lshl_b32 s4, s4, 8
	s_add_i32 s4, s4, 0x100
	v_mov_b32_e32 v2, 0
	v_mov_b32_e32 v3, 1
	v_mov_b32_e32 v0, s4
	s_nop 3
	global_atomic_add v3, v2, v3, s[2:3] sc0 sc1
	s_waitcnt lgkmcnt(0)
	s_mul_i32 s5, s5, 2
	s_add_i32 s5, s5, -1
	s_waitcnt vmcnt(0)
	v_readfirstlane_b32 s4, v3
	s_nop 3
	s_cmp_lg_u32 s4, s5
	s_cbranch_scc1 .Lfb2_poll0
	v_mov_b32_e32 v1, 1
	global_atomic_add v2, v1, s[2:3] offset:256 sc1
	global_atomic_add v2, v1, s[2:3] offset:512 sc1
	global_atomic_add v2, v1, s[2:3] offset:768 sc1
	global_atomic_add v2, v1, s[2:3] offset:1024 sc1
	global_atomic_add v2, v1, s[2:3] offset:1280 sc1
	global_atomic_add v2, v1, s[2:3] offset:1536 sc1
	global_atomic_add v2, v1, s[2:3] offset:1792 sc1
	global_atomic_add v2, v1, s[2:3] offset:2048 sc1
	s_branch .Lfb2_done

; #define WAIT_V(n) asm volatile("s_waitcnt vmcnt(" #n ")":::"memory")
; #define BAR __builtin_amdgcn_s_barrier()
; #define STAGE_A(b,h,kt) do{ unsigned char* _d = SA(b,h) + wbase; \
;     if constexpr (BLK) { const char* _s = baseA + ((size_t)(h)*(K/64) + (kt)) * 16384; GLDS(_s + voa, _d); GLDS(_s + 8192 + voa, _d + 8192); } \
;     else { const char* _s = baseA + ((size_t)(h)*128*K + (kt)*64) * 2; GLDS(_s + voa, _d); GLDS(_s + (size_t)128*K + voa, _d + 8192); } }while(0)
; #define STAGE_B(b,h,kt) do{ unsigned char* _d = SB(b,h) + wbase; \
;     if constexpr (BLK) { const char* _s = ((h)?baseB1:baseB0) + (size_t)(kt) * 16384; GLDS(_s + voa, _d); GLDS(_s + 8192 + voa, _d + 8192); } \
;     else { const char* _s = ((h)?baseB1:baseB0) + (kt)*128; GLDS(_s + voa, _d); GLDS(_s + (size_t)128*K + voa, _d + 8192); } }while(0)
; template <int K, int EPI, bool MIX = false>
; __device__ __forceinline__ void gemm_phase(const Params& p, const u16* __restrict__ A, const u16* __restrict__ Bt,
;                            const float* __restrict__ rs_in, float* __restrict__ ssq_out, float alpha, bool rev = false) {
;     ...
;   int tid = threadIdx.x;
;   asm volatile("" : "+v"(tid));
;   const int wid = __builtin_amdgcn_readfirstlane(tid >> 6);
;   const int lane = tid & 63, wr = wid >> 2, wc = wid & 3, fr = lane & 15, fq = lane >> 4;
;   const int wbase = wid * 1024;
;   int koff[2];
;   koff[0] = lds_off32(fr, fq); koff[1] = lds_off32(fr, 4 + fq);
;   int it = 0;
;   int id = item_id(0);
;   if (id >= ntiles) return;
;   if (rev) id = ntiles - 1 - id;
;   int pm, pn;
;   const char *baseA, *baseB0, *baseB1;
;   unsigned voa;
;   {
;     const int R = tid >> 3, C = ((tid & 7) ^ ((R >> 1) & 7)) * 8;
;     voa = (unsigned)(R * (BLK ? 64 : K) + C) * 2u;
;   }
;     ...
;   SETUP_TILE();
;   STAGE_B(0,0,0); STAGE_A(0,0,0); STAGE_B(0,1,0); STAGE_A(0,1,0);
;   if (wr == 1) BAR;
;   WAIT_V(4); BAR;
;   STAGE_B(1,0,1); STAGE_A(1,0,1); STAGE_B(1,1,1);
;   WAIT_V(6); BAR;
.LBB0_180:
	s_add_i32 s27, s76, 0x18000
	s_mov_b64 s[46:47], 0x80
	v_lshl_add_u64 v[8:9], v[0:1], 0, s[46:47]
	s_mov_b32 m0, s27
	s_mov_b64 s[48:49], 0x40080
	s_add_i32 s31, s76, 0x1a000
	s_waitcnt vmcnt(4)
	s_barrier
	global_load_lds_dwordx4 v[8:9], off
	v_lshl_add_u64 v[8:9], v[0:1], 0, s[48:49]
	s_mov_b32 m0, s31
	s_add_i32 s1, s76, 0x8000
	global_load_lds_dwordx4 v[8:9], off
	v_lshl_add_u64 v[8:9], v[2:3], 0, s[46:47]
	s_mov_b32 m0, s1
	s_add_i32 s34, s76, 0xa000
	global_load_lds_dwordx4 v[8:9], off
	v_lshl_add_u64 v[2:3], v[2:3], 0, s[48:49]
	s_mov_b32 m0, s34
	s_add_i32 s19, s76, 0x1c000
	s_mov_b64 s[72:73], 0x80080
	global_load_lds_dwordx4 v[2:3], off
	v_lshl_add_u64 v[2:3], v[0:1], 0, s[72:73]
	s_mov_b32 m0, s19
	s_mov_b64 s[70:71], 0xc0080
	s_add_i32 s18, s76, 0x1e000
	global_load_lds_dwordx4 v[2:3], off
	v_lshl_add_u64 v[0:1], v[0:1], 0, s[70:71]
	s_mov_b32 m0, s18
	s_and_b32 s4, s3, 3
	global_load_lds_dwordx4 v[0:1], off
	s_lshl_b32 s3, s4, 12
	s_or_b32 s5, s3, 0x10000
	s_lshl_b32 s6, s2, 13
	s_or_b32 s7, s3, 0x14000
	s_or_b32 s8, s3, 0x18000
	s_or_b32 s9, s3, 0x1c000
	s_lshl_b32 s13, s2, 6
	s_cmpk_lt_u32 s0, 0x100
	s_cselect_b64 s[2:3], -1, 0
	v_and_b32_e32 v219, 15, v6
	v_bfe_u32 v0, v6, 4, 2
	v_bfe_u32 v2, v6, 1, 3
	v_writelane_b32 v255, s2, 18
	v_lshlrev_b32_e32 v1, 7, v219
	v_xor_b32_e32 v3, v0, v2
	v_bitop3_b32 v0, v0, v2, 4 bitop3:0x36
	s_waitcnt vmcnt(6)
	v_writelane_b32 v255, s3, 19
	s_lshl_b32 s0, s4, 5
	v_lshl_or_b32 v3, v3, 4, v1
	v_lshl_or_b32 v0, v0, 4, v1
	v_writelane_b32 v255, s0, 20
	s_lshl_b32 s2, s4, 6
	v_and_b32_e32 v218, 63, v6
	s_mov_b32 s3, 0
	v_add_u32_e32 v210, v5, v4
	v_mov_b32_e32 v211, v209
	v_add_u32_e32 v220, s5, v3
	v_add_u32_e32 v221, s5, v0
	v_add_u32_e32 v222, s6, v3
	v_add_u32_e32 v223, s6, v0
	s_add_i32 s28, s76, 0xc000
	s_add_i32 s22, s76, 0xe000
	v_add_u32_e32 v224, s7, v3
	v_add_u32_e32 v225, s7, v0
	s_mov_b64 s[78:79], 0x100
	s_mov_b64 s[80:81], 0x40100
	v_add_u32_e32 v226, s8, v3
	v_add_u32_e32 v227, s8, v0
	v_add_u32_e32 v228, s9, v3
	v_add_u32_e32 v229, s9, v0
	s_mov_b64 s[82:83], 0x180
	s_mov_b64 s[96:97], 0x40180
	v_mov_b32_e32 v232, 0x358637bd
	s_mov_b32 s29, 0x800000
	s_mov_b32 s68, 0x3f3504f3
	s_mov_b32 s69, 0x3ea7ba05
	s_mov_b32 s36, 0x3f87dc22
	s_mov_b32 s30, 0x3fb5f0e3
	s_mov_b32 s0, 0xbe91a98e
	s_mov_b32 s14, 0x3e827906
	s_brev_b32 s38, -2
	s_movk_i32 s41, 0x2800
	s_lshl_b32 s24, s2, 1
	v_mbcnt_hi_u32_b32 v233, -1, v231
	v_mov_b32_e32 v234, 0x3e000000
	s_mov_b32 s74, 0
	v_writelane_b32 v255, s13, 21
	s_barrier
	v_readfirstlane_b32 vcc_lo, v230
	s_nop 3
	s_cmpk_ge_u32 vcc_lo, 0x100
	s_cbranch_scc1 .Lprio_p3
	s_setprio 1

; #define SCHED __builtin_amdgcn_sched_barrier(0)
; template <int K, int EPI, bool MIX = false>
; __device__ __forceinline__ void gemm_phase(const Params& p, const u16* __restrict__ A, const u16* __restrict__ Bt,
;                            const float* __restrict__ rs_in, float* __restrict__ ssq_out, float alpha, bool rev = false) {
;     ...
;     if (!more) break;
;     asm volatile("" ::: "memory");
;     SCHED;
;   }
;     ...
; }
.LBB0_306:
	s_setprio 0
	v_readlane_b32 s72, v255, 15
	v_readlane_b32 s68, v255, 12
	v_readlane_b32 s73, v255, 16
	v_readlane_b32 s77, v255, 17
	v_readlane_b32 s76, v255, 6
	v_readlane_b32 s70, v255, 14
	v_readlane_b32 s69, v255, 13

; #define WAIT_V(n) asm volatile("s_waitcnt vmcnt(" #n ")":::"memory")
; #define BAR __builtin_amdgcn_s_barrier()
; #define STAGE_A(b,h,kt) do{ unsigned char* _d = SA(b,h) + wbase; \
;     if constexpr (BLK) { const char* _s = baseA + ((size_t)(h)*(K/64) + (kt)) * 16384; GLDS(_s + voa, _d); GLDS(_s + 8192 + voa, _d + 8192); } \
;     else { const char* _s = baseA + ((size_t)(h)*128*K + (kt)*64) * 2; GLDS(_s + voa, _d); GLDS(_s + (size_t)128*K + voa, _d + 8192); } }while(0)
; #define STAGE_B(b,h,kt) do{ unsigned char* _d = SB(b,h) + wbase; \
;     if constexpr (BLK) { const char* _s = ((h)?baseB1:baseB0) + (size_t)(kt) * 16384; GLDS(_s + voa, _d); GLDS(_s + 8192 + voa, _d + 8192); } \
;     else { const char* _s = ((h)?baseB1:baseB0) + (kt)*128; GLDS(_s + voa, _d); GLDS(_s + (size_t)128*K + voa, _d + 8192); } }while(0)
; template <int K, int EPI, bool MIX = false>
; __device__ __forceinline__ void gemm_phase(const Params& p, const u16* __restrict__ A, const u16* __restrict__ Bt,
;                            const float* __restrict__ rs_in, float* __restrict__ ssq_out, float alpha, bool rev = false) {
;     ...
;   int tid = threadIdx.x;
;   asm volatile("" : "+v"(tid));
;   const int wid = __builtin_amdgcn_readfirstlane(tid >> 6);
;   const int lane = tid & 63, wr = wid >> 2, wc = wid & 3, fr = lane & 15, fq = lane >> 4;
;   const int wbase = wid * 1024;
;   int koff[2];
;   koff[0] = lds_off32(fr, fq); koff[1] = lds_off32(fr, 4 + fq);
;   int it = 0;
;   int id = item_id(0);
;   if (id >= ntiles) return;
;   if (rev) id = ntiles - 1 - id;
;   int pm, pn;
;   const char *baseA, *baseB0, *baseB1;
;   unsigned voa;
;   {
;     const int R = tid >> 3, C = ((tid & 7) ^ ((R >> 1) & 7)) * 8;
;     voa = (unsigned)(R * (BLK ? 64 : K) + C) * 2u;
;   }
;     ...
;   SETUP_TILE();
;   STAGE_B(0,0,0); STAGE_A(0,0,0); STAGE_B(0,1,0); STAGE_A(0,1,0);
;   if (wr == 1) BAR;
;   WAIT_V(4); BAR;
;   STAGE_B(1,0,1); STAGE_A(1,0,1); STAGE_B(1,1,1);
;   WAIT_V(6); BAR;
.LBB0_362:
	s_add_i32 s65, s34, 0x18000
	s_mov_b64 s[18:19], 0x80
	v_lshl_add_u64 v[8:9], v[0:1], 0, s[18:19]
	s_mov_b32 m0, s65
	s_mov_b64 s[20:21], 0x40080
	s_add_i32 s68, s34, 0x1a000
	s_waitcnt vmcnt(4)
	s_barrier
	global_load_lds_dwordx4 v[8:9], off
	v_lshl_add_u64 v[8:9], v[0:1], 0, s[20:21]
	s_mov_b32 m0, s68
	s_add_i32 s69, s34, 0x8000
	global_load_lds_dwordx4 v[8:9], off
	v_lshl_add_u64 v[8:9], v[2:3], 0, s[18:19]
	s_mov_b32 m0, s69
	s_add_i32 s70, s34, 0xa000
	global_load_lds_dwordx4 v[8:9], off
	v_lshl_add_u64 v[2:3], v[2:3], 0, s[20:21]
	s_mov_b32 m0, s70
	s_add_i32 s71, s34, 0x1c000
	s_mov_b64 s[22:23], 0x80080
	global_load_lds_dwordx4 v[2:3], off
	v_lshl_add_u64 v[2:3], v[0:1], 0, s[22:23]
	s_mov_b32 m0, s71
	s_mov_b64 s[24:25], 0xc0080
	s_add_i32 s72, s34, 0x1e000
	global_load_lds_dwordx4 v[2:3], off
	v_lshl_add_u64 v[0:1], v[0:1], 0, s[24:25]
	s_mov_b32 m0, s72
	s_and_b32 s6, s6, 3
	global_load_lds_dwordx4 v[0:1], off
	s_lshl_b32 s7, s6, 12
	v_and_b32_e32 v233, 15, v4
	v_bfe_u32 v0, v4, 4, 2
	v_bfe_u32 v2, v4, 1, 3
	s_or_b32 s28, s7, 0x10000
	s_lshl_b32 s30, s5, 13
	s_or_b32 s31, s7, 0x14000
	s_or_b32 s38, s7, 0x18000
	s_or_b32 s7, s7, 0x1c000
	s_lshl_b32 s73, s5, 6
	v_lshlrev_b32_e32 v1, 7, v233
	v_xor_b32_e32 v3, v0, v2
	v_bitop3_b32 v0, v0, v2, 4 bitop3:0x36
	s_waitcnt vmcnt(6)
	s_cmpk_lt_u32 s4, 0x100
	v_lshl_or_b32 v3, v3, 4, v1
	v_lshl_or_b32 v0, v0, 4, v1
	s_cselect_b64 s[26:27], -1, 0
	s_lshl_b32 s4, s6, 5
	s_mov_b32 s29, 0
	v_and_b32_e32 v232, 63, v4
	v_add_u32_e32 v222, v6, v5
	v_mov_b32_e32 v223, v221
	v_add_u32_e32 v234, s28, v3
	v_add_u32_e32 v235, s28, v0
	v_add_u32_e32 v236, s30, v3
	v_add_u32_e32 v237, s30, v0
	s_add_i32 s74, s34, 0xc000
	s_add_i32 s75, s34, 0xe000
	v_add_u32_e32 v238, s31, v3
	v_add_u32_e32 v239, s31, v0
	s_mov_b64 s[30:31], 0x100
	s_mov_b64 s[36:37], 0x40100
	v_add_u32_e32 v240, s38, v3
	v_add_u32_e32 v241, s38, v0
	v_add_u32_e32 v242, s7, v3
	v_add_u32_e32 v243, s7, v0
	s_mov_b64 s[38:39], 0x180
	s_mov_b64 s[40:41], 0x40180
	v_mov_b32_e32 v244, 0x358637bd
	s_mov_b32 s76, 0x800000
	s_mov_b64 s[46:47], 0x900
	s_mov_b64 s[48:49], 0x40900
	s_mov_b64 s[50:51], 0x980
	s_mov_b64 s[58:59], 0x40980
	v_mbcnt_hi_u32_b32 v245, -1, v231
	s_lshl_b32 s28, s4, 1
	s_mov_b32 s77, s29
	s_barrier
	v_readfirstlane_b32 vcc_lo, v230
	s_nop 3
	s_cmpk_ge_u32 vcc_lo, 0x100
	s_cbranch_scc1 .Lprio_p5
	s_setprio 1

; #define SCHED __builtin_amdgcn_sched_barrier(0)
; template <int K, int EPI, bool MIX = false>
; __device__ __forceinline__ void gemm_phase(const Params& p, const u16* __restrict__ A, const u16* __restrict__ Bt,
;                            const float* __restrict__ rs_in, float* __restrict__ ssq_out, float alpha, bool rev = false) {
;     ...
;     if (!more) break;
;     asm volatile("" ::: "memory");
;     SCHED;
;   }
;     ...
; }
.LBB0_406:
	s_setprio 0
	s_mov_b64 s[72:73], s[52:53]
	s_mov_b32 s77, s56
	s_mov_b32 s76, s57
	v_readlane_b32 s68, v255, 12
	s_mov_b32 s70, s54
	v_readlane_b32 s69, v255, 13

; #define WAIT_V(n) asm volatile("s_waitcnt vmcnt(" #n ")":::"memory")
; #define BAR __builtin_amdgcn_s_barrier()
; #define STAGE_A(b,h,kt) do{ unsigned char* _d = SA(b,h) + wbase; \
;     if constexpr (BLK) { const char* _s = baseA + ((size_t)(h)*(K/64) + (kt)) * 16384; GLDS(_s + voa, _d); GLDS(_s + 8192 + voa, _d + 8192); } \
;     else { const char* _s = baseA + ((size_t)(h)*128*K + (kt)*64) * 2; GLDS(_s + voa, _d); GLDS(_s + (size_t)128*K + voa, _d + 8192); } }while(0)
; #define STAGE_B(b,h,kt) do{ unsigned char* _d = SB(b,h) + wbase; \
;     if constexpr (BLK) { const char* _s = ((h)?baseB1:baseB0) + (size_t)(kt) * 16384; GLDS(_s + voa, _d); GLDS(_s + 8192 + voa, _d + 8192); } \
;     else { const char* _s = ((h)?baseB1:baseB0) + (kt)*128; GLDS(_s + voa, _d); GLDS(_s + (size_t)128*K + voa, _d + 8192); } }while(0)
; template <int K, int EPI, bool MIX = false>
; __device__ __forceinline__ void gemm_phase(const Params& p, const u16* __restrict__ A, const u16* __restrict__ Bt,
;                            const float* __restrict__ rs_in, float* __restrict__ ssq_out, float alpha, bool rev = false) {
;     ...
;   int tid = threadIdx.x;
;   asm volatile("" : "+v"(tid));
;   const int wid = __builtin_amdgcn_readfirstlane(tid >> 6);
;   const int lane = tid & 63, wr = wid >> 2, wc = wid & 3, fr = lane & 15, fq = lane >> 4;
;   const int wbase = wid * 1024;
;   int koff[2];
;   koff[0] = lds_off32(fr, fq); koff[1] = lds_off32(fr, 4 + fq);
;   int it = 0;
;   int id = item_id(0);
;   if (id >= ntiles) return;
;   if (rev) id = ntiles - 1 - id;
;   int pm, pn;
;   const char *baseA, *baseB0, *baseB1;
;   unsigned voa;
;   {
;     const int R = tid >> 3, C = ((tid & 7) ^ ((R >> 1) & 7)) * 8;
;     voa = (unsigned)(R * (BLK ? 64 : K) + C) * 2u;
;   }
;     ...
;   SETUP_TILE();
;   STAGE_B(0,0,0); STAGE_A(0,0,0); STAGE_B(0,1,0); STAGE_A(0,1,0);
;   if (wr == 1) BAR;
;   WAIT_V(4); BAR;
;   STAGE_B(1,0,1); STAGE_A(1,0,1); STAGE_B(1,1,1);
;   WAIT_V(6); BAR;
.LBB0_420:
	s_add_i32 s62, s33, 0x18000
	s_mov_b64 s[16:17], 0x80
	v_lshl_add_u64 v[10:11], v[0:1], 0, s[16:17]
	s_mov_b32 m0, s62
	s_mov_b64 s[18:19], 0x40080
	s_add_i32 s63, s33, 0x1a000
	s_waitcnt vmcnt(4)
	s_barrier
	global_load_lds_dwordx4 v[10:11], off
	v_lshl_add_u64 v[0:1], v[0:1], 0, s[18:19]
	s_mov_b32 m0, s63
	s_add_i32 s64, s33, 0x8000
	global_load_lds_dwordx4 v[0:1], off
	v_lshl_add_u64 v[0:1], v[2:3], 0, s[16:17]
	s_mov_b32 m0, s64
	s_add_i32 s65, s33, 0xa000
	global_load_lds_dwordx4 v[0:1], off
	v_lshl_add_u64 v[0:1], v[2:3], 0, s[18:19]
	s_mov_b32 m0, s65
	s_add_i32 s68, s33, 0x1c000
	global_load_lds_dwordx4 v[0:1], off
	v_lshl_add_u64 v[0:1], v[4:5], 0, s[16:17]
	s_mov_b32 m0, s68
	s_add_i32 s69, s33, 0x1e000
	global_load_lds_dwordx4 v[0:1], off
	v_lshl_add_u64 v[0:1], v[4:5], 0, s[18:19]
	s_mov_b32 m0, s69
	s_and_b32 s22, s20, 3
	global_load_lds_dwordx4 v[0:1], off
	s_lshl_b32 s20, s22, 12
	s_or_b32 s24, s20, 0x10000
	s_lshl_b32 s25, s5, 13
	s_or_b32 s28, s20, 0x14000
	s_or_b32 s36, s20, 0x18000
	s_or_b32 s40, s20, 0x1c000
	s_lshl_b32 s70, s5, 6
	v_and_b32_e32 v223, 15, v8
	v_bfe_u32 v0, v8, 4, 2
	v_bfe_u32 v2, v8, 1, 3
	s_cmpk_lt_u32 s4, 0x100
	v_lshlrev_b32_e32 v1, 7, v223
	v_xor_b32_e32 v3, v0, v2
	v_bitop3_b32 v0, v0, v2, 4 bitop3:0x36
	s_waitcnt vmcnt(6)
	s_cselect_b64 s[20:21], -1, 0
	s_lshl_b32 s71, s22, 5
	v_lshl_or_b32 v3, v3, 4, v1
	v_lshl_or_b32 v0, v0, 4, v1
	s_and_b32 s4, s71, 32
	s_mov_b32 s23, 0
	v_and_b32_e32 v222, 63, v8
	v_add_u32_e32 v216, v7, v6
	v_mov_b32_e32 v217, v215
	v_add_u32_e32 v224, s24, v3
	v_add_u32_e32 v225, s24, v0
	v_add_u32_e32 v226, s25, v3
	v_add_u32_e32 v227, s25, v0
	s_mov_b64 s[24:25], 0x80080
	s_add_i32 s72, s33, 0xc000
	s_mov_b64 s[26:27], 0xc0080
	s_add_i32 s73, s33, 0xe000
	v_add_u32_e32 v228, s28, v3
	v_add_u32_e32 v229, s28, v0
	s_mov_b64 s[28:29], 0x100
	s_mov_b64 s[30:31], 0x40100
	v_add_u32_e32 v232, s36, v3
	v_add_u32_e32 v233, s36, v0
	s_mov_b64 s[36:37], 0x80100
	s_mov_b64 s[38:39], 0xc0100
	v_add_u32_e32 v234, s40, v3
	v_add_u32_e32 v235, s40, v0
	s_mov_b64 s[40:41], 0x180
	s_mov_b64 s[46:47], 0x40180
	s_mov_b64 s[48:49], 0x80f80
	s_mov_b64 s[50:51], 0xc0f80
	v_mov_b32_e32 v236, 0x358637bd
	s_mov_b32 s74, 0x800000
	s_lshl_b32 s22, s4, 1
	s_mov_b32 s75, s23
	s_barrier
	v_readfirstlane_b32 vcc_lo, v230
	s_nop 3
	s_cmpk_ge_u32 vcc_lo, 0x100
	s_cbranch_scc1 .Lprio_p6
	s_setprio 1

; #define SCHED __builtin_amdgcn_sched_barrier(0)
; template <int K, int EPI, bool MIX = false>
; __device__ __forceinline__ void gemm_phase(const Params& p, const u16* __restrict__ A, const u16* __restrict__ Bt,
;                            const float* __restrict__ rs_in, float* __restrict__ ssq_out, float alpha, bool rev = false) {
;     ...
;     if (!more) break;
;     asm volatile("" ::: "memory");
;     SCHED;
;   }
;     ...
; }
.LBB0_446:
	s_setprio 0
	s_mov_b64 s[72:73], s[54:55]
	s_mov_b32 s77, s56
	s_mov_b32 s76, s57
	v_readlane_b32 s68, v255, 12
	v_readlane_b32 s69, v255, 13

; #define WAIT_V(n) asm volatile("s_waitcnt vmcnt(" #n ")":::"memory")
; #define BAR __builtin_amdgcn_s_barrier()
; #define STAGE_A(b,h,kt) do{ unsigned char* _d = SA(b,h) + wbase; \
;     if constexpr (BLK) { const char* _s = baseA + ((size_t)(h)*(K/64) + (kt)) * 16384; GLDS(_s + voa, _d); GLDS(_s + 8192 + voa, _d + 8192); } \
;     else { const char* _s = baseA + ((size_t)(h)*128*K + (kt)*64) * 2; GLDS(_s + voa, _d); GLDS(_s + (size_t)128*K + voa, _d + 8192); } }while(0)
; #define STAGE_B(b,h,kt) do{ unsigned char* _d = SB(b,h) + wbase; \
;     if constexpr (BLK) { const char* _s = ((h)?baseB1:baseB0) + (size_t)(kt) * 16384; GLDS(_s + voa, _d); GLDS(_s + 8192 + voa, _d + 8192); } \
;     else { const char* _s = ((h)?baseB1:baseB0) + (kt)*128; GLDS(_s + voa, _d); GLDS(_s + (size_t)128*K + voa, _d + 8192); } }while(0)
; template <int K, int EPI, bool MIX = false>
; __device__ __forceinline__ void gemm_phase(const Params& p, const u16* __restrict__ A, const u16* __restrict__ Bt,
;                            const float* __restrict__ rs_in, float* __restrict__ ssq_out, float alpha, bool rev = false) {
;     ...
;   int tid = threadIdx.x;
;   asm volatile("" : "+v"(tid));
;   const int wid = __builtin_amdgcn_readfirstlane(tid >> 6);
;   const int lane = tid & 63, wr = wid >> 2, wc = wid & 3, fr = lane & 15, fq = lane >> 4;
;   const int wbase = wid * 1024;
;   int koff[2];
;   koff[0] = lds_off32(fr, fq); koff[1] = lds_off32(fr, 4 + fq);
;   int it = 0;
;   int id = item_id(0);
;   if (id >= ntiles) return;
;   if (rev) id = ntiles - 1 - id;
;   int pm, pn;
;   const char *baseA, *baseB0, *baseB1;
;   unsigned voa;
;   {
;     const int R = tid >> 3, C = ((tid & 7) ^ ((R >> 1) & 7)) * 8;
;     voa = (unsigned)(R * (BLK ? 64 : K) + C) * 2u;
;   }
;     ...
;   SETUP_TILE();
;   STAGE_B(0,0,0); STAGE_A(0,0,0); STAGE_B(0,1,0); STAGE_A(0,1,0);
;   if (wr == 1) BAR;
;   WAIT_V(4); BAR;
;   STAGE_B(1,0,1); STAGE_A(1,0,1); STAGE_B(1,1,1);
;   WAIT_V(6); BAR;
.LBB0_460:
	s_add_i32 s55, s33, 0x18000
	s_mov_b64 s[14:15], 0x4000
	v_lshl_add_u64 v[8:9], v[0:1], 0, s[14:15]
	s_mov_b32 m0, s55
	s_mov_b64 s[16:17], 0x6000
	s_add_i32 s58, s33, 0x1a000
	s_waitcnt vmcnt(4)
	s_barrier
	global_load_lds_dwordx4 v[8:9], off
	v_lshl_add_u64 v[8:9], v[0:1], 0, s[16:17]
	s_mov_b32 m0, s58
	s_add_i32 s59, s33, 0x8000
	global_load_lds_dwordx4 v[8:9], off
	v_lshl_add_u64 v[8:9], v[2:3], 0, s[14:15]
	s_mov_b32 m0, s59
	s_add_i32 s60, s33, 0xa000
	global_load_lds_dwordx4 v[8:9], off
	v_lshl_add_u64 v[2:3], v[2:3], 0, s[16:17]
	s_mov_b32 m0, s60
	s_add_i32 s61, s33, 0x1c000
	s_mov_b64 s[18:19], 0x164000
	global_load_lds_dwordx4 v[2:3], off
	v_lshl_add_u64 v[2:3], v[0:1], 0, s[18:19]
	s_mov_b32 m0, s61
	s_mov_b64 s[20:21], 0x166000
	s_add_i32 s62, s33, 0x1e000
	global_load_lds_dwordx4 v[2:3], off
	v_lshl_add_u64 v[0:1], v[0:1], 0, s[20:21]
	s_mov_b32 m0, s62
	s_and_b32 s24, s22, 3
	global_load_lds_dwordx4 v[0:1], off
	s_lshl_b32 s22, s24, 12
	v_and_b32_e32 v0, 15, v6
	v_bfe_u32 v1, v6, 4, 2
	v_bfe_u32 v2, v6, 1, 3
	s_or_b32 s26, s22, 0x10000
	s_lshl_b32 s27, s3, 13
	s_or_b32 s28, s22, 0x14000
	s_or_b32 s30, s22, 0x18000
	s_or_b32 s38, s22, 0x1c000
	v_lshlrev_b32_e32 v0, 7, v0
	v_xor_b32_e32 v3, v1, v2
	v_bitop3_b32 v1, v1, v2, 4 bitop3:0x36
	s_waitcnt vmcnt(6)
	s_cmpk_lt_u32 s2, 0x100
	v_lshl_or_b32 v3, v3, 4, v0
	v_lshl_or_b32 v0, v1, 4, v0
	s_cselect_b64 s[22:23], -1, 0
	s_lshl_b32 s2, s24, 5
	s_mov_b32 s25, 0
	v_and_b32_e32 v224, 63, v6
	s_lshl_b32 s63, s3, 6
	v_add_u32_e32 v218, v5, v4
	v_mov_b32_e32 v219, v217
	v_add_u32_e32 v225, s26, v3
	v_add_u32_e32 v226, s26, v0
	v_add_u32_e32 v227, s27, v3
	v_add_u32_e32 v228, s27, v0
	s_add_i32 s64, s33, 0xc000
	s_add_i32 s65, s33, 0xe000
	v_add_u32_e32 v229, s28, v3
	v_add_u32_e32 v232, s28, v0
	s_mov_b64 s[26:27], 0x8000
	s_mov_b64 s[28:29], 0xa000
	v_add_u32_e32 v233, s30, v3
	v_add_u32_e32 v234, s30, v0
	s_mov_b64 s[30:31], 0x168000
	s_mov_b64 s[36:37], 0x16a000
	v_add_u32_e32 v235, s38, v3
	v_add_u32_e32 v236, s38, v0
	s_mov_b64 s[38:39], 0xc000
	s_mov_b64 s[40:41], 0xe000
	s_mov_b64 s[46:47], 0x2bc000
	s_mov_b64 s[48:49], 0x2be000
	v_mbcnt_hi_u32_b32 v231, -1, v231
	s_lshl_b32 s24, s2, 1
	s_mov_b32 s66, s25
	s_barrier
	v_readfirstlane_b32 vcc_lo, v230
	s_nop 3
	s_cmpk_ge_u32 vcc_lo, 0x100
	s_cbranch_scc1 .Lprio_p7
	s_setprio 1

; #define SCHED __builtin_amdgcn_sched_barrier(0)
; template <int K, int EPI, bool MIX = false>
; __device__ __forceinline__ void gemm_phase(const Params& p, const u16* __restrict__ A, const u16* __restrict__ Bt,
;                            const float* __restrict__ rs_in, float* __restrict__ ssq_out, float alpha, bool rev = false) {
;     ...
;     if (!more) break;
;     asm volatile("" ::: "memory");
;     SCHED;
;   }
;     ...
; }
.LBB0_502:
	s_setprio 0
	v_readlane_b32 s68, v255, 12
	v_readlane_b32 s69, v255, 13
